# mc_item<0/1> epilogues: the 4 gate loads issued together up front (carry-chain address adds rewritten as 64-bit adds), stores no longer waited between groups
# speedup vs baseline: 1.0060x; 1.0060x over previous
; __device__ __forceinline__ float siluf(float x) { return x * __builtin_amdgcn_rcpf(1.0f + __expf(-x)); }
; #define BSYNC() do { asm volatile("s_waitcnt vmcnt(0) lgkmcnt(0)" ::: "memory"); __syncthreads(); } while (0)
; template <int TY> __device__ __forceinline__ void mc_item(const Params& p, ldsp lds, int item) {
;     ...
;     BSYNC();
; #pragma unroll
;     for (int tk = 0; tk < 4; ++tk) { float s = 0.f;
; #pragma unroll
;         for (int w = 0; w < 8; ++w) s += RED[w * 64 + 16 * tk + l15];
;         rstd[tk] = rsqrtf(s * (1.0f / DV) + EPS); }
;     const float* nwp = TY == 0 ? p.in[12] : (TY == 1 ? p.in[14] : p.in[17]);
;     const int goff = TY == 0 ? E_RA + h * 128 : (TY == 1 ? E_GB + h * 128 : O_G + h * 512);
;     constexpr int LDY = TY == 2 ? 2048 : 1024; const int ycol = TY == 0 ? h * 128 : (TY == 1 ? 512 + h * 128 : h * 512);
;     bf16_t* Y = (bf16_t*)(p.ws + WS_Y);
; #pragma unroll
;     for (int ei = 0; ei < ET; ++ei) { const int e0 = 16 * (wave * ET + ei) + 4 * q4; const f32x4 w4 = *(const f32x4*)(nwp + e0);
; #pragma unroll
;         for (int tk = 0; tk < 4; ++tk) { const size_t row = (size_t)row0 + 16 * tk + l15;
;             const u32x2 gw = *(const u32x2*)(Pb + row * PP + goff + e0);
;             const float g0 = bf2f(gw.x & 0xffffu), g1 = bf2f(gw.x >> 16), g2 = bf2f(gw.y & 0xffffu), g3 = bf2f(gw.y >> 16);
;             const f32x4 v = acc[ei][tk] * rstd[tk] * w4;
;             float y0 = v[0] * siluf(g0), y1 = v[1] * siluf(g1), y2 = v[2] * siluf(g2), y3 = v[3] * siluf(g3);
.LBB0_1239:
	s_or_b64 exec, exec, s[0:1]
	s_lshl_b32 s9, s15, 1
	s_add_u32 s0, s26, s9
	v_or_b32_e32 v18, s12, v28
	s_addc_u32 s1, s27, 0
	v_or_b32_e32 v22, s16, v30
	s_waitcnt lgkmcnt(0)
	v_ashrrev_i32_e32 v19, 31, v18
	v_mov_b64_e32 v[28:29], s[0:1]
	v_lshlrev_b64 v[26:27], 1, v[18:19]
	v_mad_i64_i32 v[24:25], s[0:1], v22, s55, v[28:29]
	v_lshl_add_u64 v[24:25], v[24:25], 0, v[26:27]
	s_waitcnt vmcnt(0) lgkmcnt(0)
	s_barrier
	global_load_dwordx2 v[48:49], v[24:25], off offset:2048
	v_readlane_b32 s76, v252, 20
	v_readlane_b32 s84, v252, 28
	v_readlane_b32 s85, v252, 29
	v_lshl_add_u32 v16, v30, 2, 0
	v_add_u32_e32 v32, 0xd800, v16
	v_lshl_add_u64 v[20:21], v[18:19], 2, s[84:85]
	global_load_dwordx4 v[18:21], v[20:21], off
	v_or_b32_e32 v134, 16, v22
	v_mad_i64_i32 v[140:141], s[0:1], v134, s55, v[28:29]
	v_lshl_add_u64 v[142:143], v[140:141], 0, v[26:27]
	global_load_dwordx2 v[144:145], v[142:143], off offset:2048
	v_or_b32_e32 v146, 32, v22
	v_mad_i64_i32 v[148:149], s[0:1], v146, s55, v[28:29]
	v_lshl_add_u64 v[150:151], v[148:149], 0, v[26:27]
	v_or_b32_e32 v152, 48, v22
	global_load_dwordx2 v[154:155], v[150:151], off offset:2048
	v_mad_i64_i32 v[156:157], s[0:1], v152, s55, v[28:29]
	v_lshl_add_u64 v[166:167], v[156:157], 0, v[26:27]
	global_load_dwordx2 v[168:169], v[166:167], off offset:2048
	v_add_u32_e32 v16, 0xdc00, v16
	ds_read2_b32 v[24:25], v32 offset1:16
	ds_read2_b32 v[50:51], v32 offset0:64 offset1:80
	ds_read2_b32 v[52:53], v32 offset0:128 offset1:144
	ds_read2_b32 v[54:55], v32 offset0:192 offset1:208
	ds_read2_b32 v[56:57], v16 offset1:16
	ds_read2_b32 v[58:59], v16 offset0:64 offset1:80
	ds_read2_b32 v[60:61], v16 offset0:128 offset1:144
	ds_read2_b32 v[62:63], v16 offset0:192 offset1:208
	ds_read2_b32 v[46:47], v32 offset0:32 offset1:48
	ds_read2_b32 v[44:45], v32 offset0:96 offset1:112
	ds_read2_b32 v[42:43], v32 offset0:160 offset1:176
	ds_read2_b32 v[40:41], v32 offset0:224 offset1:240
	ds_read2_b32 v[38:39], v16 offset0:32 offset1:48
	ds_read2_b32 v[36:37], v16 offset0:96 offset1:112
	ds_read2_b32 v[34:35], v16 offset0:160 offset1:176
	ds_read2_b32 v[32:33], v16 offset0:224 offset1:240
	s_waitcnt lgkmcnt(14)
	v_mov_b32_e32 v64, v25
	v_mov_b32_e32 v65, v24
	v_mov_b32_e32 v24, v51
	v_mov_b32_e32 v25, v50
	s_waitcnt lgkmcnt(13)
	v_mov_b32_e32 v50, v53
	v_mov_b32_e32 v51, v52
	s_waitcnt lgkmcnt(12)
	v_mov_b32_e32 v52, v55
	v_mov_b32_e32 v53, v54
	s_waitcnt lgkmcnt(11)
	v_mov_b32_e32 v54, v57
	v_mov_b32_e32 v55, v56
	s_waitcnt lgkmcnt(10)
	v_mov_b32_e32 v56, v59
	v_mov_b32_e32 v57, v58
	s_waitcnt lgkmcnt(9)
	v_mov_b32_e32 v58, v61
	v_mov_b32_e32 v59, v60
	s_waitcnt lgkmcnt(8)
	v_mov_b32_e32 v60, v63
	v_mov_b32_e32 v61, v62
	v_pk_add_f32 v[62:63], v[64:65], 0 op_sel_hi:[1,0]
	s_mov_b32 s0, 0x358637bd
	v_pk_add_f32 v[24:25], v[62:63], v[24:25]
	v_mov_b64_e32 v[30:31], s[0:1]
	v_pk_add_f32 v[24:25], v[24:25], v[50:51]
	v_mov_b32_e32 v23, s8
	v_pk_add_f32 v[24:25], v[24:25], v[52:53]
	s_brev_b32 s8, 60
	v_pk_add_f32 v[24:25], v[24:25], v[54:55]
	s_add_u32 s0, s61, s9
	v_pk_add_f32 v[24:25], v[24:25], v[56:57]
	v_readlane_b32 s1, v253, 31
	v_pk_add_f32 v[24:25], v[24:25], v[58:59]
	s_addc_u32 s1, s1, 0
	v_pk_add_f32 v[24:25], v[24:25], v[60:61]
	v_readlane_b32 s77, v252, 21
	v_pk_fma_f32 v[50:51], v[24:25], s[8:9], v[30:31] op_sel_hi:[1,0,0]
	v_lshl_add_u64 v[24:25], s[0:1], 0, v[26:27]
	v_mul_f32_e32 v16, 0x4b800000, v51
	v_cmp_gt_f32_e32 vcc, s33, v51
	v_readlane_b32 s78, v252, 22
	v_readlane_b32 s79, v252, 23
	v_cndmask_b32_e32 v16, v51, v16, vcc
	v_rsq_f32_e32 v16, v16
	v_readlane_b32 s80, v252, 24
	v_readlane_b32 s81, v252, 25
	v_readlane_b32 s82, v252, 26
	v_mul_f32_e32 v51, 0x45800000, v16
	v_cndmask_b32_e32 v16, v16, v51, vcc
	v_pk_mul_f32 v[12:13], v[12:13], v[16:17] op_sel_hi:[1,0]
	v_pk_mul_f32 v[14:15], v[14:15], v[16:17] op_sel_hi:[1,0]
	v_cmp_gt_f32_e32 vcc, s33, v50
	v_readlane_b32 s83, v252, 27
	v_readlane_b32 s86, v252, 30
	v_readlane_b32 s87, v252, 31
	v_readlane_b32 s88, v252, 32
	v_readlane_b32 s89, v252, 33
	v_readlane_b32 s90, v252, 34
	v_readlane_b32 s91, v252, 35
	s_waitcnt vmcnt(0)
; __device__ __forceinline__ unsigned pk2(float lo, float hi) { return pg8::cvt_pk_bf16(lo, hi); }
; __device__ __forceinline__ float siluf(float x) { return x * __builtin_amdgcn_rcpf(1.0f + __expf(-x)); }
; template <int TY> __device__ __forceinline__ void mc_item(const Params& p, ldsp lds, int item) {
;     ...
;     for (int ei = 0; ei < ET; ++ei) { const int e0 = 16 * (wave * ET + ei) + 4 * q4; const f32x4 w4 = *(const f32x4*)(nwp + e0);
; #pragma unroll
;         for (int tk = 0; tk < 4; ++tk) { const size_t row = (size_t)row0 + 16 * tk + l15;
;             const u32x2 gw = *(const u32x2*)(Pb + row * PP + goff + e0);
;             const float g0 = bf2f(gw.x & 0xffffu), g1 = bf2f(gw.x >> 16), g2 = bf2f(gw.y & 0xffffu), g3 = bf2f(gw.y >> 16);
;             const f32x4 v = acc[ei][tk] * rstd[tk] * w4;
;             float y0 = v[0] * siluf(g0), y1 = v[1] * siluf(g1), y2 = v[2] * siluf(g2), y3 = v[3] * siluf(g3);
;     ...
;             if (!(fabsf(y0) < 1e30f)) y0 = 0.f; if (!(fabsf(y1) < 1e30f)) y1 = 0.f; if (!(fabsf(y2) < 1e30f)) y2 = 0.f; if (!(fabsf(y3) < 1e30f)) y3 = 0.f;
;     ...
;             u32x2 o; o.x = pk2(y0, y1); o.y = pk2(y2, y3);
;             *(u32x2*)(Y + row * LDY + ycol + e0) = o; } }
	v_lshlrev_b32_e32 v16, 16, v48
	v_mul_f32_e32 v52, 0xbfb8aa3b, v16
	v_exp_f32_e32 v52, v52
	v_and_b32_e32 v48, 0xffff0000, v48
	v_lshlrev_b32_e32 v51, 16, v49
	v_and_b32_e32 v49, 0xffff0000, v49
	v_mul_f32_e32 v53, 0xbfb8aa3b, v48
	v_mul_f32_e32 v54, 0xbfb8aa3b, v51
	v_mul_f32_e32 v55, 0xbfb8aa3b, v49
	v_exp_f32_e32 v53, v53
	v_add_f32_e32 v52, 1.0, v52
	v_exp_f32_e32 v54, v54
	v_exp_f32_e32 v55, v55
	v_rcp_f32_e32 v52, v52
	v_add_f32_e32 v53, 1.0, v53
	v_pk_mul_f32 v[12:13], v[12:13], v[18:19]
	v_add_f32_e32 v54, 1.0, v54
	v_rcp_f32_e32 v53, v53
	v_add_f32_e32 v55, 1.0, v55
	v_mul_f32_e32 v16, v52, v16
	v_rcp_f32_e32 v54, v54
	v_mul_f32_e32 v12, v12, v16
	v_rcp_f32_e32 v16, v55
	v_mul_f32_e32 v48, v53, v48
	v_pk_mul_f32 v[14:15], v[14:15], v[20:21]
	v_mul_f32_e32 v13, v13, v48
	v_mul_f32_e32 v48, v54, v51
	v_mul_f32_e32 v16, v16, v49
	v_mul_f32_e32 v14, v14, v48
	v_mul_f32_e32 v15, v15, v16
	v_cvt_pk_bf16_f32 v12, v12, v13
	v_cvt_pk_bf16_f32 v13, v14, v15
	v_lshlrev_b64 v[14:15], 11, v[22:23]
	v_lshl_add_u64 v[14:15], v[24:25], 0, v[14:15]
	global_store_dwordx2 v[14:15], v[12:13], off
	v_or_b32_e32 v12, 16, v22
	v_mad_i64_i32 v[14:15], s[0:1], v12, s55, v[28:29]
	v_lshl_add_u64 v[14:15], v[14:15], 0, v[26:27]
	v_mul_f32_e32 v16, 0x4b800000, v50
	v_cndmask_b32_e32 v16, v50, v16, vcc
	v_rsq_f32_e32 v16, v16
	v_mov_b32_e32 v13, v23
	v_or_b32_e32 v48, 32, v22
	v_lshlrev_b64 v[12:13], 11, v[12:13]
	v_mul_f32_e32 v49, 0x45800000, v16
	v_cndmask_b32_e32 v16, v16, v49, vcc
	v_pk_mul_f32 v[8:9], v[8:9], v[16:17] op_sel_hi:[1,0]
	v_pk_mul_f32 v[10:11], v[10:11], v[16:17] op_sel_hi:[1,0]
	v_pk_mul_f32 v[8:9], v[8:9], v[18:19]
	v_mad_i64_i32 v[50:51], s[0:1], v48, s55, v[28:29]
	v_lshl_add_u64 v[12:13], v[24:25], 0, v[12:13]
	v_pk_mul_f32 v[10:11], v[10:11], v[20:21]
	v_lshl_add_u64 v[50:51], v[50:51], 0, v[26:27]
	v_or_b32_e32 v22, 48, v22
	v_lshlrev_b32_e32 v16, 16, v144
	v_and_b32_e32 v14, 0xffff0000, v144
	v_lshlrev_b32_e32 v49, 16, v145
	v_and_b32_e32 v15, 0xffff0000, v145
	v_mul_f32_e32 v52, 0xbfb8aa3b, v16
	v_mul_f32_e32 v53, 0xbfb8aa3b, v14
	v_mul_f32_e32 v54, 0xbfb8aa3b, v49
	v_mul_f32_e32 v55, 0xbfb8aa3b, v15
	v_exp_f32_e32 v52, v52
	v_exp_f32_e32 v53, v53
	v_exp_f32_e32 v54, v54
	v_exp_f32_e32 v55, v55
	v_add_f32_e32 v52, 1.0, v52
	v_add_f32_e32 v53, 1.0, v53
	v_add_f32_e32 v54, 1.0, v54
	v_add_f32_e32 v55, 1.0, v55
	v_rcp_f32_e32 v52, v52
	v_rcp_f32_e32 v53, v53
	v_rcp_f32_e32 v54, v54
	v_rcp_f32_e32 v55, v55
	v_mul_f32_e32 v16, v52, v16
	v_mul_f32_e32 v14, v53, v14
	v_mul_f32_e32 v49, v54, v49
	v_mul_f32_e32 v15, v55, v15
	v_mul_f32_e32 v8, v8, v16
	v_mul_f32_e32 v9, v9, v14
	v_mul_f32_e32 v10, v10, v49
	v_mul_f32_e32 v11, v11, v15
	v_cvt_pk_bf16_f32 v8, v8, v9
	v_cvt_pk_bf16_f32 v9, v10, v11
	global_store_dwordx2 v[12:13], v[8:9], off
	s_waitcnt lgkmcnt(7)
	v_mov_b32_e32 v12, v47
	v_mov_b32_e32 v13, v46
	s_waitcnt lgkmcnt(6)
	v_mov_b32_e32 v14, v45
	v_mov_b32_e32 v15, v44
	v_pk_add_f32 v[12:13], v[12:13], 0 op_sel_hi:[1,0]
	s_waitcnt lgkmcnt(5)
	v_mov_b32_e32 v44, v43
	v_mov_b32_e32 v45, v42
	v_pk_add_f32 v[12:13], v[12:13], v[14:15]
	s_waitcnt lgkmcnt(4)
	v_mov_b32_e32 v42, v41
	v_mov_b32_e32 v43, v40
	v_pk_add_f32 v[12:13], v[12:13], v[44:45]
	s_waitcnt lgkmcnt(3)
	v_mov_b32_e32 v40, v39
	v_mov_b32_e32 v41, v38
	v_pk_add_f32 v[12:13], v[12:13], v[42:43]
	s_waitcnt lgkmcnt(2)
	v_mov_b32_e32 v38, v37
	v_mov_b32_e32 v39, v36
	v_pk_add_f32 v[12:13], v[12:13], v[40:41]
	s_waitcnt lgkmcnt(1)
	v_mov_b32_e32 v36, v35
	v_mov_b32_e32 v37, v34
	v_pk_add_f32 v[12:13], v[12:13], v[38:39]
	s_waitcnt lgkmcnt(0)
	v_mov_b32_e32 v34, v33
	v_mov_b32_e32 v35, v32
	v_pk_add_f32 v[12:13], v[12:13], v[36:37]
	v_mov_b32_e32 v49, v23
	v_pk_add_f32 v[12:13], v[12:13], v[34:35]
	v_lshlrev_b64 v[10:11], 11, v[48:49]
	v_pk_fma_f32 v[12:13], v[12:13], s[8:9], v[30:31] op_sel_hi:[1,0,0]
	v_lshl_add_u64 v[10:11], v[24:25], 0, v[10:11]
	v_mul_f32_e32 v14, 0x4b800000, v13
	v_cmp_gt_f32_e32 vcc, s33, v13
	s_nop 1
	v_cndmask_b32_e32 v13, v13, v14, vcc
	v_rsq_f32_e32 v13, v13
	v_mad_i64_i32 v[14:15], s[0:1], v22, s55, v[28:29]
	v_lshl_add_u64 v[14:15], v[14:15], 0, v[26:27]
	v_mul_f32_e32 v16, 0x45800000, v13
	v_cndmask_b32_e32 v16, v13, v16, vcc
	v_pk_mul_f32 v[4:5], v[4:5], v[16:17] op_sel_hi:[1,0]
	v_pk_mul_f32 v[6:7], v[6:7], v[16:17] op_sel_hi:[1,0]
	v_pk_mul_f32 v[4:5], v[18:19], v[4:5]
	v_pk_mul_f32 v[6:7], v[20:21], v[6:7]
	v_cmp_gt_f32_e32 vcc, s33, v12
	v_lshlrev_b32_e32 v13, 16, v154
	v_and_b32_e32 v8, 0xffff0000, v154
	v_lshlrev_b32_e32 v16, 16, v155
	v_and_b32_e32 v9, 0xffff0000, v155
	v_mul_f32_e32 v26, 0xbfb8aa3b, v13
	v_mul_f32_e32 v27, 0xbfb8aa3b, v8
	v_mul_f32_e32 v28, 0xbfb8aa3b, v16
	v_mul_f32_e32 v29, 0xbfb8aa3b, v9
	v_exp_f32_e32 v26, v26
	v_exp_f32_e32 v27, v27
	v_exp_f32_e32 v28, v28
	v_exp_f32_e32 v29, v29
	v_add_f32_e32 v26, 1.0, v26
	v_add_f32_e32 v27, 1.0, v27
	v_add_f32_e32 v28, 1.0, v28
	v_add_f32_e32 v29, 1.0, v29
	v_rcp_f32_e32 v26, v26
	v_rcp_f32_e32 v27, v27
	v_rcp_f32_e32 v28, v28
	v_rcp_f32_e32 v29, v29
	v_mul_f32_e32 v13, v26, v13
	v_mul_f32_e32 v8, v27, v8
	v_mul_f32_e32 v16, v28, v16
	v_mul_f32_e32 v9, v29, v9
	v_mul_f32_e32 v4, v4, v13
	v_mul_f32_e32 v5, v5, v8
	v_mul_f32_e32 v6, v6, v16
	v_mul_f32_e32 v7, v7, v9
	v_cvt_pk_bf16_f32 v4, v4, v5
	v_cvt_pk_bf16_f32 v5, v6, v7
	global_store_dwordx2 v[10:11], v[4:5], off
	v_mul_f32_e32 v6, 0x4b800000, v12
	v_cndmask_b32_e32 v6, v12, v6, vcc
	v_rsq_f32_e32 v8, v6
	v_lshlrev_b64 v[6:7], 11, v[22:23]
	v_mul_f32_e32 v9, 0x45800000, v8
	v_cndmask_b32_e32 v8, v8, v9, vcc
	v_pk_mul_f32 v[0:1], v[0:1], v[8:9] op_sel_hi:[1,0]
	v_pk_mul_f32 v[2:3], v[2:3], v[8:9] op_sel_hi:[1,0]
	v_pk_mul_f32 v[0:1], v[18:19], v[0:1]
	v_pk_mul_f32 v[2:3], v[20:21], v[2:3]
	v_lshlrev_b32_e32 v8, 16, v168
	v_and_b32_e32 v4, 0xffff0000, v168
	v_lshlrev_b32_e32 v9, 16, v169
	v_and_b32_e32 v5, 0xffff0000, v169
	v_mul_f32_e32 v10, 0xbfb8aa3b, v8
	v_mul_f32_e32 v11, 0xbfb8aa3b, v4
	v_mul_f32_e32 v12, 0xbfb8aa3b, v9
	v_mul_f32_e32 v13, 0xbfb8aa3b, v5
	v_exp_f32_e32 v10, v10
	v_exp_f32_e32 v11, v11
	v_exp_f32_e32 v12, v12
	v_exp_f32_e32 v13, v13
	v_add_f32_e32 v10, 1.0, v10
	v_add_f32_e32 v11, 1.0, v11
	v_add_f32_e32 v12, 1.0, v12
	v_add_f32_e32 v13, 1.0, v13
	v_rcp_f32_e32 v10, v10
	v_rcp_f32_e32 v11, v11
	v_rcp_f32_e32 v12, v12
	v_rcp_f32_e32 v13, v13
	v_mul_f32_e32 v8, v10, v8
	v_mul_f32_e32 v4, v11, v4
	v_mul_f32_e32 v9, v12, v9
	v_mul_f32_e32 v5, v13, v5
	v_mul_f32_e32 v0, v0, v8
	v_mul_f32_e32 v1, v1, v4
	v_mul_f32_e32 v2, v2, v9
	v_mul_f32_e32 v3, v3, v5
	v_cvt_pk_bf16_f32 v0, v0, v1
	v_cvt_pk_bf16_f32 v1, v2, v3
	v_lshl_add_u64 v[2:3], v[24:25], 0, v[6:7]
	global_store_dwordx2 v[2:3], v[0:1], off
	s_waitcnt vmcnt(0) lgkmcnt(0)
	s_barrier

; __device__ __forceinline__ float siluf(float x) { return x * __builtin_amdgcn_rcpf(1.0f + __expf(-x)); }
; #define BSYNC() do { asm volatile("s_waitcnt vmcnt(0) lgkmcnt(0)" ::: "memory"); __syncthreads(); } while (0)
; template <int TY> __device__ __forceinline__ void mc_item(const Params& p, ldsp lds, int item) {
;     ...
;     BSYNC();
; #pragma unroll
;     for (int tk = 0; tk < 4; ++tk) { float s = 0.f;
; #pragma unroll
;         for (int w = 0; w < 8; ++w) s += RED[w * 64 + 16 * tk + l15];
;         rstd[tk] = rsqrtf(s * (1.0f / DV) + EPS); }
;     const float* nwp = TY == 0 ? p.in[12] : (TY == 1 ? p.in[14] : p.in[17]);
;     const int goff = TY == 0 ? E_RA + h * 128 : (TY == 1 ? E_GB + h * 128 : O_G + h * 512);
;     constexpr int LDY = TY == 2 ? 2048 : 1024; const int ycol = TY == 0 ? h * 128 : (TY == 1 ? 512 + h * 128 : h * 512);
;     bf16_t* Y = (bf16_t*)(p.ws + WS_Y);
; #pragma unroll
;     for (int ei = 0; ei < ET; ++ei) { const int e0 = 16 * (wave * ET + ei) + 4 * q4; const f32x4 w4 = *(const f32x4*)(nwp + e0);
; #pragma unroll
;         for (int tk = 0; tk < 4; ++tk) { const size_t row = (size_t)row0 + 16 * tk + l15;
;             const u32x2 gw = *(const u32x2*)(Pb + row * PP + goff + e0);
;             const float g0 = bf2f(gw.x & 0xffffu), g1 = bf2f(gw.x >> 16), g2 = bf2f(gw.y & 0xffffu), g3 = bf2f(gw.y >> 16);
;             const f32x4 v = acc[ei][tk] * rstd[tk] * w4;
;             float y0 = v[0] * siluf(g0), y1 = v[1] * siluf(g1), y2 = v[2] * siluf(g2), y3 = v[3] * siluf(g3);
.LBB0_1254:
	s_or_b64 exec, exec, s[0:1]
	v_lshl_add_u32 v8, v24, 2, 0
	v_add_u32_e32 v16, 0x13800, v8
	v_or_b32_e32 v22, s17, v24
	s_waitcnt vmcnt(0) lgkmcnt(0)
	s_waitcnt lgkmcnt(0)
	s_barrier
	ds_read2_b32 v[8:9], v16 offset1:16
	ds_read2_b32 v[10:11], v16 offset0:64 offset1:80
	ds_read2_b32 v[24:25], v16 offset0:128 offset1:144
	ds_read2_b32 v[26:27], v16 offset0:192 offset1:208
	v_add_u32_e32 v40, 0x400, v16
	s_waitcnt lgkmcnt(3)
	v_mov_b32_e32 v36, v9
	v_mov_b32_e32 v37, v8
	v_pk_add_f32 v[8:9], v[36:37], 0 op_sel_hi:[1,0]
	s_waitcnt lgkmcnt(2)
	v_mov_b32_e32 v36, v11
	v_mov_b32_e32 v37, v10
	ds_read2_b32 v[28:29], v40 offset1:16
	ds_read2_b32 v[30:31], v40 offset0:64 offset1:80
	ds_read2_b32 v[32:33], v40 offset0:128 offset1:144
	ds_read2_b32 v[34:35], v40 offset0:192 offset1:208
	v_pk_add_f32 v[8:9], v[8:9], v[36:37]
	s_waitcnt lgkmcnt(5)
	v_mov_b32_e32 v10, v25
	v_mov_b32_e32 v11, v24
	v_pk_add_f32 v[8:9], v[8:9], v[10:11]
	s_waitcnt lgkmcnt(4)
	v_mov_b32_e32 v10, v27
	v_mov_b32_e32 v11, v26
	v_pk_add_f32 v[8:9], v[8:9], v[10:11]
	s_waitcnt lgkmcnt(3)
	v_mov_b32_e32 v10, v29
	v_mov_b32_e32 v11, v28
	v_pk_add_f32 v[8:9], v[8:9], v[10:11]
	s_waitcnt lgkmcnt(2)
	v_mov_b32_e32 v10, v31
	v_mov_b32_e32 v11, v30
	v_pk_add_f32 v[8:9], v[8:9], v[10:11]
	s_waitcnt lgkmcnt(1)
	v_mov_b32_e32 v10, v33
	v_mov_b32_e32 v11, v32
	v_pk_add_f32 v[8:9], v[8:9], v[10:11]
	s_waitcnt lgkmcnt(0)
	v_mov_b32_e32 v10, v35
	v_mov_b32_e32 v11, v34
	s_mov_b32 s0, 0x358637bd
	v_pk_add_f32 v[8:9], v[8:9], v[10:11]
	v_mov_b64_e32 v[10:11], s[0:1]
	s_brev_b32 s18, 60
	v_pk_fma_f32 v[8:9], v[8:9], s[18:19], v[10:11] op_sel_hi:[1,0,0]
	v_readlane_b32 s76, v252, 20
	v_mul_f32_e32 v24, 0x4b800000, v9
	v_cmp_gt_f32_e64 s[0:1], s33, v9
	v_cmp_gt_f32_e32 vcc, s33, v8
	v_readlane_b32 s88, v252, 32
	v_cndmask_b32_e64 v9, v9, v24, s[0:1]
	v_rsq_f32_e32 v9, v9
	v_readlane_b32 s89, v252, 33
	v_readlane_b32 s77, v252, 21
	v_readlane_b32 s78, v252, 22
	v_mul_f32_e32 v24, 0x45800000, v9
	v_cndmask_b32_e64 v32, v9, v24, s[0:1]
	v_mul_f32_e32 v9, 0x4b800000, v8
	v_cndmask_b32_e32 v8, v8, v9, vcc
	v_rsq_f32_e32 v8, v8
	v_readlane_b32 s79, v252, 23
	v_readlane_b32 s80, v252, 24
	v_readlane_b32 s81, v252, 25
	v_mul_f32_e32 v9, 0x45800000, v8
	v_cndmask_b32_e32 v30, v8, v9, vcc
	ds_read2_b32 v[8:9], v16 offset0:32 offset1:48
	ds_read2_b32 v[24:25], v16 offset0:96 offset1:112
	ds_read2_b32 v[26:27], v16 offset0:160 offset1:176
	ds_read2_b32 v[28:29], v16 offset0:224 offset1:240
	ds_read2_b32 v[34:35], v40 offset0:32 offset1:48
	ds_read2_b32 v[36:37], v40 offset0:96 offset1:112
	ds_read2_b32 v[38:39], v40 offset0:160 offset1:176
	ds_read2_b32 v[40:41], v40 offset0:224 offset1:240
	s_waitcnt lgkmcnt(7)
	v_mov_b32_e32 v42, v9
	v_mov_b32_e32 v43, v8
	v_pk_add_f32 v[8:9], v[42:43], 0 op_sel_hi:[1,0]
	s_waitcnt lgkmcnt(6)
	v_mov_b32_e32 v42, v25
	v_mov_b32_e32 v43, v24
	v_pk_add_f32 v[8:9], v[8:9], v[42:43]
	s_waitcnt lgkmcnt(5)
	v_mov_b32_e32 v24, v27
	v_mov_b32_e32 v25, v26
	v_pk_add_f32 v[8:9], v[8:9], v[24:25]
	s_waitcnt lgkmcnt(4)
	v_mov_b32_e32 v24, v29
	v_mov_b32_e32 v25, v28
	v_pk_add_f32 v[8:9], v[8:9], v[24:25]
	s_waitcnt lgkmcnt(3)
	v_mov_b32_e32 v24, v35
	v_mov_b32_e32 v25, v34
	v_pk_add_f32 v[8:9], v[8:9], v[24:25]
	s_waitcnt lgkmcnt(2)
	v_mov_b32_e32 v24, v37
	v_mov_b32_e32 v25, v36
	v_pk_add_f32 v[8:9], v[8:9], v[24:25]
	s_waitcnt lgkmcnt(1)
	v_mov_b32_e32 v24, v39
	v_mov_b32_e32 v25, v38
	v_pk_add_f32 v[8:9], v[8:9], v[24:25]
	s_waitcnt lgkmcnt(0)
	v_mov_b32_e32 v24, v41
	v_mov_b32_e32 v25, v40
	v_pk_add_f32 v[8:9], v[8:9], v[24:25]
	v_or_b32_e32 v24, s13, v23
	v_pk_fma_f32 v[8:9], v[8:9], s[18:19], v[10:11] op_sel_hi:[1,0,0]
	s_add_u32 s18, s26, s16
	v_mul_f32_e32 v10, 0x4b800000, v9
	v_cmp_gt_f32_e64 s[0:1], s33, v9
	v_cmp_gt_f32_e32 vcc, s33, v8
	s_addc_u32 s19, s27, 0
	v_cndmask_b32_e64 v9, v9, v10, s[0:1]
	v_rsq_f32_e32 v9, v9
	v_ashrrev_i32_e32 v25, 31, v24
	v_mov_b64_e32 v[28:29], s[18:19]
	v_mov_b32_e32 v23, s9
	v_mul_f32_e32 v10, 0x45800000, v9
	v_cndmask_b32_e64 v26, v9, v10, s[0:1]
	v_mul_f32_e32 v9, 0x4b800000, v8
	v_cndmask_b32_e32 v8, v8, v9, vcc
	v_rsq_f32_e32 v8, v8
	s_add_u32 s0, s68, s16
	v_mad_i64_i32 v[34:35], s[16:17], v22, s55, v[28:29]
	v_mul_f32_e32 v9, 0x45800000, v8
	v_cndmask_b32_e32 v16, v8, v9, vcc
	v_lshl_add_u64 v[8:9], v[24:25], 2, s[88:89]
	v_lshlrev_b64 v[24:25], 1, v[24:25]
	v_lshl_add_u64 v[34:35], v[34:35], 0, v[24:25]
	v_add_co_u32_e32 v34, vcc, s57, v34
	global_load_dwordx4 v[8:11], v[8:9], off
	s_nop 0
	v_addc_co_u32_e32 v35, vcc, 0, v35, vcc
	global_load_dwordx2 v[34:35], v[34:35], off offset:2048
	s_mov_b32 s98, s57
	s_mov_b32 s99, 0
	v_or_b32_e32 v64, 16, v22
	v_mad_i64_i32 v[134:135], s[16:17], v64, s55, v[28:29]
	v_lshl_add_u64 v[140:141], v[134:135], 0, v[24:25]
	v_lshl_add_u64 v[142:143], v[140:141], 0, s[98:99]
	global_load_dwordx2 v[144:145], v[142:143], off offset:2048
	v_or_b32_e32 v146, 32, v22
	v_mad_i64_i32 v[148:149], s[16:17], v146, s55, v[28:29]
	v_lshl_add_u64 v[150:151], v[148:149], 0, v[24:25]
	v_lshl_add_u64 v[152:153], v[150:151], 0, s[98:99]
	global_load_dwordx2 v[154:155], v[152:153], off offset:2048
	v_or_b32_e32 v156, 48, v22
	v_mad_i64_i32 v[166:167], s[16:17], v156, s55, v[28:29]
	v_lshl_add_u64 v[168:169], v[166:167], 0, v[24:25]
	v_lshl_add_u64 v[172:173], v[168:169], 0, s[98:99]
	global_load_dwordx2 v[174:175], v[172:173], off offset:2048
	s_addc_u32 s1, s69, 0
	s_mov_b32 s9, 0x1ec21000
	v_pk_mul_f32 v[0:1], v[0:1], v[16:17] op_sel_hi:[1,0]
	v_pk_mul_f32 v[2:3], v[2:3], v[16:17] op_sel_hi:[1,0]
	v_readlane_b32 s82, v252, 26
	v_readlane_b32 s83, v252, 27
	v_readlane_b32 s84, v252, 28
	v_readlane_b32 s85, v252, 29
	v_readlane_b32 s86, v252, 30
	v_readlane_b32 s87, v252, 31
	v_readlane_b32 s90, v252, 34
	v_readlane_b32 s91, v252, 35
	s_waitcnt vmcnt(0)
; __device__ __forceinline__ unsigned pk2(float lo, float hi) { return pg8::cvt_pk_bf16(lo, hi); }
; __device__ __forceinline__ float siluf(float x) { return x * __builtin_amdgcn_rcpf(1.0f + __expf(-x)); }
; template <int TY> __device__ __forceinline__ void mc_item(const Params& p, ldsp lds, int item) {
;     ...
;     for (int ei = 0; ei < ET; ++ei) { const int e0 = 16 * (wave * ET + ei) + 4 * q4; const f32x4 w4 = *(const f32x4*)(nwp + e0);
; #pragma unroll
;         for (int tk = 0; tk < 4; ++tk) { const size_t row = (size_t)row0 + 16 * tk + l15;
;             const u32x2 gw = *(const u32x2*)(Pb + row * PP + goff + e0);
;             const float g0 = bf2f(gw.x & 0xffffu), g1 = bf2f(gw.x >> 16), g2 = bf2f(gw.y & 0xffffu), g3 = bf2f(gw.y >> 16);
;             const f32x4 v = acc[ei][tk] * rstd[tk] * w4;
;             float y0 = v[0] * siluf(g0), y1 = v[1] * siluf(g1), y2 = v[2] * siluf(g2), y3 = v[3] * siluf(g3);
;     ...
;             if (!(fabsf(y0) < 1e30f)) y0 = 0.f; if (!(fabsf(y1) < 1e30f)) y1 = 0.f; if (!(fabsf(y2) < 1e30f)) y2 = 0.f; if (!(fabsf(y3) < 1e30f)) y3 = 0.f;
;     ...
;             u32x2 o; o.x = pk2(y0, y1); o.y = pk2(y2, y3);
;             *(u32x2*)(Y + row * LDY + ycol + e0) = o; } }
	v_pk_mul_f32 v[0:1], v[8:9], v[0:1]
	v_pk_mul_f32 v[2:3], v[10:11], v[2:3]
	v_lshlrev_b32_e32 v27, 16, v34
	v_lshlrev_b32_e32 v33, 16, v35
	v_pk_mul_f32 v[18:19], v[18:19], v[32:33] op_sel_hi:[1,0]
	v_pk_mul_f32 v[20:21], v[20:21], v[32:33] op_sel_hi:[1,0]
	v_mul_f32_e32 v32, 0xbfb8aa3b, v27
	v_exp_f32_e32 v32, v32
	v_and_b32_e32 v31, 0xffff0000, v34
	v_pk_mul_f32 v[18:19], v[18:19], v[8:9]
	v_and_b32_e32 v34, 0xffff0000, v35
	v_add_f32_e32 v32, 1.0, v32
	v_rcp_f32_e32 v32, v32
	v_pk_mul_f32 v[20:21], v[20:21], v[10:11]
	v_mul_f32_e32 v27, v32, v27
	v_mul_f32_e32 v18, v18, v27
	v_mul_f32_e32 v27, 0xbfb8aa3b, v31
	v_exp_f32_e32 v27, v27
	s_nop 0
	v_add_f32_e32 v27, 1.0, v27
	v_rcp_f32_e32 v27, v27
	s_nop 0
	v_mul_f32_e32 v27, v27, v31
	v_mul_f32_e32 v19, v19, v27
	v_mul_f32_e32 v27, 0xbfb8aa3b, v33
	v_exp_f32_e32 v27, v27
	v_cvt_pk_bf16_f32 v18, v18, v19
	s_nop 0
	v_add_f32_e32 v27, 1.0, v27
	v_rcp_f32_e32 v27, v27
	s_nop 0
	v_mul_f32_e32 v27, v27, v33
	v_mul_f32_e32 v20, v20, v27
	v_mul_f32_e32 v27, 0xbfb8aa3b, v34
	v_exp_f32_e32 v27, v27
	s_nop 0
	v_add_f32_e32 v27, 1.0, v27
	v_rcp_f32_e32 v27, v27
	s_nop 0
	v_mul_f32_e32 v27, v27, v34
	v_mul_f32_e32 v21, v21, v27
	v_cvt_pk_bf16_f32 v19, v20, v21
	v_lshlrev_b64 v[20:21], 11, v[22:23]
	v_lshl_add_u64 v[20:21], s[0:1], 0, v[20:21]
	v_lshl_add_u64 v[20:21], v[20:21], 0, v[24:25]
	v_add_co_u32_e32 v20, vcc, s9, v20
	s_nop 1
	v_addc_co_u32_e32 v21, vcc, 0, v21, vcc
	global_store_dwordx2 v[20:21], v[18:19], off offset:1024
	v_or_b32_e32 v18, 16, v22
	v_mad_i64_i32 v[20:21], s[16:17], v18, s55, v[28:29]
	v_lshl_add_u64 v[20:21], v[20:21], 0, v[24:25]
	s_nop 0
	v_mov_b32_e32 v19, v23
	s_nop 0
	v_lshl_add_u64 v[20:21], v[20:21], 0, s[98:99]
	v_lshlrev_b32_e32 v27, 16, v144
	v_lshlrev_b32_e32 v31, 16, v145
	v_pk_mul_f32 v[12:13], v[12:13], v[30:31] op_sel_hi:[1,0]
	v_pk_mul_f32 v[14:15], v[14:15], v[30:31] op_sel_hi:[1,0]
	v_mul_f32_e32 v30, 0xbfb8aa3b, v27
	v_exp_f32_e32 v30, v30
	v_and_b32_e32 v20, 0xffff0000, v144
	v_pk_mul_f32 v[12:13], v[12:13], v[8:9]
	v_and_b32_e32 v21, 0xffff0000, v145
	v_add_f32_e32 v30, 1.0, v30
	v_rcp_f32_e32 v30, v30
	v_pk_mul_f32 v[14:15], v[14:15], v[10:11]
	v_mul_f32_e32 v27, v30, v27
	v_mul_f32_e32 v12, v12, v27
	v_mul_f32_e32 v27, 0xbfb8aa3b, v20
	v_exp_f32_e32 v27, v27
	s_nop 0
	v_add_f32_e32 v27, 1.0, v27
	v_rcp_f32_e32 v27, v27
	s_nop 0
	v_mul_f32_e32 v20, v27, v20
	v_mul_f32_e32 v13, v13, v20
	v_mul_f32_e32 v20, 0xbfb8aa3b, v31
	v_exp_f32_e32 v20, v20
	v_cvt_pk_bf16_f32 v12, v12, v13
	v_pk_mul_f32 v[4:5], v[4:5], v[26:27] op_sel_hi:[1,0]
	v_pk_mul_f32 v[6:7], v[6:7], v[26:27] op_sel_hi:[1,0]
	v_add_f32_e32 v20, 1.0, v20
	v_rcp_f32_e32 v20, v20
	v_pk_mul_f32 v[4:5], v[8:9], v[4:5]
	v_pk_mul_f32 v[6:7], v[10:11], v[6:7]
	v_mul_f32_e32 v20, v20, v31
	v_mul_f32_e32 v14, v14, v20
	v_mul_f32_e32 v20, 0xbfb8aa3b, v21
	v_exp_f32_e32 v20, v20
	s_nop 0
	v_add_f32_e32 v20, 1.0, v20
	v_rcp_f32_e32 v20, v20
	s_nop 0
	v_mul_f32_e32 v20, v20, v21
	v_mul_f32_e32 v15, v15, v20
	v_cvt_pk_bf16_f32 v13, v14, v15
	v_lshlrev_b64 v[14:15], 11, v[18:19]
	v_lshl_add_u64 v[14:15], s[0:1], 0, v[14:15]
	v_lshl_add_u64 v[14:15], v[14:15], 0, v[24:25]
	v_add_co_u32_e32 v14, vcc, s9, v14
	s_nop 1
	v_addc_co_u32_e32 v15, vcc, 0, v15, vcc
	global_store_dwordx2 v[14:15], v[12:13], off offset:1024
	v_or_b32_e32 v12, 32, v22
	v_mad_i64_i32 v[14:15], s[16:17], v12, s55, v[28:29]
	v_lshl_add_u64 v[14:15], v[14:15], 0, v[24:25]
	s_nop 0
	v_mov_b32_e32 v13, v23
	s_nop 0
	v_lshl_add_u64 v[14:15], v[14:15], 0, s[98:99]
	v_or_b32_e32 v22, 48, v22
	v_lshlrev_b32_e32 v18, 16, v154
	v_mul_f32_e32 v20, 0xbfb8aa3b, v18
	v_exp_f32_e32 v20, v20
	v_and_b32_e32 v14, 0xffff0000, v154
	v_lshlrev_b32_e32 v19, 16, v155
	v_and_b32_e32 v15, 0xffff0000, v155
	v_add_f32_e32 v20, 1.0, v20
	v_rcp_f32_e32 v20, v20
	s_nop 0
	v_mul_f32_e32 v18, v20, v18
	v_mul_f32_e32 v4, v4, v18
	v_mul_f32_e32 v18, 0xbfb8aa3b, v14
	v_exp_f32_e32 v18, v18
	s_nop 0
	v_add_f32_e32 v18, 1.0, v18
	v_rcp_f32_e32 v18, v18
	s_nop 0
	v_mul_f32_e32 v14, v18, v14
	v_mul_f32_e32 v5, v5, v14
	v_mul_f32_e32 v14, 0xbfb8aa3b, v19
	v_exp_f32_e32 v14, v14
	v_cvt_pk_bf16_f32 v4, v4, v5
	s_nop 0
	v_add_f32_e32 v14, 1.0, v14
	v_rcp_f32_e32 v14, v14
	s_nop 0
	v_mul_f32_e32 v14, v14, v19
	v_mul_f32_e32 v6, v6, v14
	v_mul_f32_e32 v14, 0xbfb8aa3b, v15
	v_exp_f32_e32 v14, v14
	s_nop 0
	v_add_f32_e32 v14, 1.0, v14
	v_rcp_f32_e32 v14, v14
	s_nop 0
	v_mul_f32_e32 v14, v14, v15
	v_mul_f32_e32 v7, v7, v14
	v_cvt_pk_bf16_f32 v5, v6, v7
	v_lshlrev_b64 v[6:7], 11, v[12:13]
	v_lshl_add_u64 v[6:7], s[0:1], 0, v[6:7]
	v_lshl_add_u64 v[6:7], v[6:7], 0, v[24:25]
	v_add_co_u32_e32 v6, vcc, s9, v6
	s_nop 1
	v_addc_co_u32_e32 v7, vcc, 0, v7, vcc
	global_store_dwordx2 v[6:7], v[4:5], off offset:1024
	v_mad_i64_i32 v[4:5], s[16:17], v22, s55, v[28:29]
	v_lshl_add_u64 v[4:5], v[4:5], 0, v[24:25]
	s_nop 0
	s_nop 1
	v_lshl_add_u64 v[4:5], v[4:5], 0, s[98:99]
	v_lshlrev_b32_e32 v6, 16, v174
	v_mul_f32_e32 v8, 0xbfb8aa3b, v6
	v_exp_f32_e32 v8, v8
	v_and_b32_e32 v4, 0xffff0000, v174
	v_lshlrev_b32_e32 v7, 16, v175
	v_and_b32_e32 v5, 0xffff0000, v175
	v_add_f32_e32 v8, 1.0, v8
	v_rcp_f32_e32 v8, v8
	s_nop 0
	v_mul_f32_e32 v6, v8, v6
	v_mul_f32_e32 v0, v0, v6
	v_mul_f32_e32 v6, 0xbfb8aa3b, v4
	v_exp_f32_e32 v6, v6
	s_nop 0
	v_add_f32_e32 v6, 1.0, v6
	v_rcp_f32_e32 v6, v6
	s_nop 0
	v_mul_f32_e32 v4, v6, v4
	v_mul_f32_e32 v1, v1, v4
	v_mul_f32_e32 v4, 0xbfb8aa3b, v7
	v_exp_f32_e32 v4, v4
	v_cvt_pk_bf16_f32 v0, v0, v1
	s_nop 0
	v_add_f32_e32 v4, 1.0, v4
	v_rcp_f32_e32 v4, v4
	s_nop 0
	v_mul_f32_e32 v4, v4, v7
	v_mul_f32_e32 v2, v2, v4
	v_mul_f32_e32 v4, 0xbfb8aa3b, v5
	v_exp_f32_e32 v4, v4
	s_nop 0
	v_add_f32_e32 v4, 1.0, v4
	v_rcp_f32_e32 v4, v4
	s_nop 0
	v_mul_f32_e32 v4, v4, v5
	v_mul_f32_e32 v3, v3, v4
	v_cvt_pk_bf16_f32 v1, v2, v3
	v_lshlrev_b64 v[2:3], 11, v[22:23]
	v_lshl_add_u64 v[2:3], s[0:1], 0, v[2:3]
	v_lshl_add_u64 v[2:3], v[2:3], 0, v[24:25]
	v_add_co_u32_e32 v2, vcc, 0x1ec21000, v2
	s_nop 1
	v_addc_co_u32_e32 v3, vcc, 0, v3, vcc
	global_store_dwordx2 v[2:3], v[0:1], off offset:1024
	s_waitcnt vmcnt(0) lgkmcnt(0)
	s_barrier
	s_branch .LBB0_1240

; __device__ __forceinline__ float siluf(float x) { return x * __builtin_amdgcn_rcpf(1.0f + __expf(-x)); }
; #define BSYNC() do { asm volatile("s_waitcnt vmcnt(0) lgkmcnt(0)" ::: "memory"); __syncthreads(); } while (0)
; template <int TY> __device__ __forceinline__ void mc_item(const Params& p, ldsp lds, int item) {
;     ...
;     BSYNC();
; #pragma unroll
;     for (int tk = 0; tk < 4; ++tk) { float s = 0.f;
; #pragma unroll
;         for (int w = 0; w < 8; ++w) s += RED[w * 64 + 16 * tk + l15];
;         rstd[tk] = rsqrtf(s * (1.0f / DV) + EPS); }
;     const float* nwp = TY == 0 ? p.in[12] : (TY == 1 ? p.in[14] : p.in[17]);
;     const int goff = TY == 0 ? E_RA + h * 128 : (TY == 1 ? E_GB + h * 128 : O_G + h * 512);
;     constexpr int LDY = TY == 2 ? 2048 : 1024; const int ycol = TY == 0 ? h * 128 : (TY == 1 ? 512 + h * 128 : h * 512);
;     bf16_t* Y = (bf16_t*)(p.ws + WS_Y);
; #pragma unroll
;     for (int ei = 0; ei < ET; ++ei) { const int e0 = 16 * (wave * ET + ei) + 4 * q4; const f32x4 w4 = *(const f32x4*)(nwp + e0);
; #pragma unroll
;         for (int tk = 0; tk < 4; ++tk) { const size_t row = (size_t)row0 + 16 * tk + l15;
;             const u32x2 gw = *(const u32x2*)(Pb + row * PP + goff + e0);
;             const float g0 = bf2f(gw.x & 0xffffu), g1 = bf2f(gw.x >> 16), g2 = bf2f(gw.y & 0xffffu), g3 = bf2f(gw.y >> 16);
;             const f32x4 v = acc[ei][tk] * rstd[tk] * w4;
;             float y0 = v[0] * siluf(g0), y1 = v[1] * siluf(g1), y2 = v[2] * siluf(g2), y3 = v[3] * siluf(g3);
.LBB0_1266:
	s_or_b64 exec, exec, s[0:1]
	s_lshl_b32 s9, s9, 1
	s_add_u32 s0, s26, s9
	v_or_b32_e32 v18, s10, v28
	s_addc_u32 s1, s27, 0
	v_or_b32_e32 v22, s11, v30
	s_waitcnt lgkmcnt(0)
	v_ashrrev_i32_e32 v19, 31, v18
	v_mov_b64_e32 v[28:29], s[0:1]
	v_lshlrev_b64 v[26:27], 1, v[18:19]
	v_mad_i64_i32 v[24:25], s[0:1], v22, s55, v[28:29]
	v_lshl_add_u64 v[24:25], v[24:25], 0, v[26:27]
	s_waitcnt vmcnt(0) lgkmcnt(0)
	s_barrier
	global_load_dwordx2 v[48:49], v[24:25], off offset:2048
	v_readlane_b32 s76, v252, 20
	v_readlane_b32 s84, v252, 28
	v_readlane_b32 s85, v252, 29
	v_lshl_add_u32 v16, v30, 2, 0
	v_add_u32_e32 v32, 0xd800, v16
	v_lshl_add_u64 v[20:21], v[18:19], 2, s[84:85]
	global_load_dwordx4 v[18:21], v[20:21], off
	v_or_b32_e32 v134, 16, v22
	v_mad_i64_i32 v[140:141], s[0:1], v134, s55, v[28:29]
	v_lshl_add_u64 v[142:143], v[140:141], 0, v[26:27]
	global_load_dwordx2 v[144:145], v[142:143], off offset:2048
	v_or_b32_e32 v146, 32, v22
	v_mad_i64_i32 v[148:149], s[0:1], v146, s55, v[28:29]
	v_lshl_add_u64 v[150:151], v[148:149], 0, v[26:27]
	v_or_b32_e32 v152, 48, v22
	global_load_dwordx2 v[154:155], v[150:151], off offset:2048
	v_mad_i64_i32 v[156:157], s[0:1], v152, s55, v[28:29]
	v_lshl_add_u64 v[166:167], v[156:157], 0, v[26:27]
	global_load_dwordx2 v[168:169], v[166:167], off offset:2048
	v_add_u32_e32 v16, 0xdc00, v16
	ds_read2_b32 v[24:25], v32 offset1:16
	ds_read2_b32 v[50:51], v32 offset0:64 offset1:80
	ds_read2_b32 v[52:53], v32 offset0:128 offset1:144
	ds_read2_b32 v[54:55], v32 offset0:192 offset1:208
	ds_read2_b32 v[56:57], v16 offset1:16
	ds_read2_b32 v[58:59], v16 offset0:64 offset1:80
	ds_read2_b32 v[60:61], v16 offset0:128 offset1:144
	ds_read2_b32 v[62:63], v16 offset0:192 offset1:208
	ds_read2_b32 v[46:47], v32 offset0:32 offset1:48
	ds_read2_b32 v[44:45], v32 offset0:96 offset1:112
	ds_read2_b32 v[42:43], v32 offset0:160 offset1:176
	ds_read2_b32 v[40:41], v32 offset0:224 offset1:240
	ds_read2_b32 v[38:39], v16 offset0:32 offset1:48
	ds_read2_b32 v[36:37], v16 offset0:96 offset1:112
	ds_read2_b32 v[34:35], v16 offset0:160 offset1:176
	ds_read2_b32 v[32:33], v16 offset0:224 offset1:240
	s_waitcnt lgkmcnt(14)
	v_mov_b32_e32 v64, v25
	v_mov_b32_e32 v65, v24
	v_mov_b32_e32 v24, v51
	v_mov_b32_e32 v25, v50
	s_waitcnt lgkmcnt(13)
	v_mov_b32_e32 v50, v53
	v_mov_b32_e32 v51, v52
	s_waitcnt lgkmcnt(12)
	v_mov_b32_e32 v52, v55
	v_mov_b32_e32 v53, v54
	s_waitcnt lgkmcnt(11)
	v_mov_b32_e32 v54, v57
	v_mov_b32_e32 v55, v56
	s_waitcnt lgkmcnt(10)
	v_mov_b32_e32 v56, v59
	v_mov_b32_e32 v57, v58
	s_waitcnt lgkmcnt(9)
	v_mov_b32_e32 v58, v61
	v_mov_b32_e32 v59, v60
	s_waitcnt lgkmcnt(8)
	v_mov_b32_e32 v60, v63
	v_mov_b32_e32 v61, v62
	v_pk_add_f32 v[62:63], v[64:65], 0 op_sel_hi:[1,0]
	s_mov_b32 s0, 0x358637bd
	v_pk_add_f32 v[24:25], v[62:63], v[24:25]
	v_mov_b64_e32 v[30:31], s[0:1]
	v_pk_add_f32 v[24:25], v[24:25], v[50:51]
	s_brev_b32 s10, 60
	v_pk_add_f32 v[24:25], v[24:25], v[52:53]
	s_add_u32 s0, s61, s9
	v_pk_add_f32 v[24:25], v[24:25], v[54:55]
	v_readlane_b32 s1, v253, 31
	v_pk_add_f32 v[24:25], v[24:25], v[56:57]
	v_mov_b32_e32 v23, s13
	v_pk_add_f32 v[24:25], v[24:25], v[58:59]
	s_addc_u32 s1, s1, 0
	v_pk_add_f32 v[24:25], v[24:25], v[60:61]
	v_readlane_b32 s77, v252, 21
	v_pk_fma_f32 v[50:51], v[24:25], s[10:11], v[30:31] op_sel_hi:[1,0,0]
	v_lshl_add_u64 v[24:25], s[0:1], 0, v[26:27]
	v_mul_f32_e32 v16, 0x4b800000, v51
	v_cmp_gt_f32_e32 vcc, s33, v51
	v_readlane_b32 s78, v252, 22
	v_readlane_b32 s79, v252, 23
	v_cndmask_b32_e32 v16, v51, v16, vcc
	v_rsq_f32_e32 v16, v16
	v_readlane_b32 s80, v252, 24
	v_readlane_b32 s81, v252, 25
	v_readlane_b32 s82, v252, 26
	v_mul_f32_e32 v51, 0x45800000, v16
	v_cndmask_b32_e32 v16, v16, v51, vcc
	v_pk_mul_f32 v[12:13], v[12:13], v[16:17] op_sel_hi:[1,0]
	v_pk_mul_f32 v[14:15], v[14:15], v[16:17] op_sel_hi:[1,0]
	v_cmp_gt_f32_e32 vcc, s33, v50
	v_readlane_b32 s83, v252, 27
	v_readlane_b32 s86, v252, 30
	v_readlane_b32 s87, v252, 31
	v_readlane_b32 s88, v252, 32
	v_readlane_b32 s89, v252, 33
	v_readlane_b32 s90, v252, 34
	v_readlane_b32 s91, v252, 35
	s_waitcnt vmcnt(0)
; __device__ __forceinline__ unsigned pk2(float lo, float hi) { return pg8::cvt_pk_bf16(lo, hi); }
; __device__ __forceinline__ float siluf(float x) { return x * __builtin_amdgcn_rcpf(1.0f + __expf(-x)); }
; template <int TY> __device__ __forceinline__ void mc_item(const Params& p, ldsp lds, int item) {
;     ...
;     for (int ei = 0; ei < ET; ++ei) { const int e0 = 16 * (wave * ET + ei) + 4 * q4; const f32x4 w4 = *(const f32x4*)(nwp + e0);
; #pragma unroll
;         for (int tk = 0; tk < 4; ++tk) { const size_t row = (size_t)row0 + 16 * tk + l15;
;             const u32x2 gw = *(const u32x2*)(Pb + row * PP + goff + e0);
;             const float g0 = bf2f(gw.x & 0xffffu), g1 = bf2f(gw.x >> 16), g2 = bf2f(gw.y & 0xffffu), g3 = bf2f(gw.y >> 16);
;             const f32x4 v = acc[ei][tk] * rstd[tk] * w4;
;             float y0 = v[0] * siluf(g0), y1 = v[1] * siluf(g1), y2 = v[2] * siluf(g2), y3 = v[3] * siluf(g3);
;     ...
;             if (!(fabsf(y0) < 1e30f)) y0 = 0.f; if (!(fabsf(y1) < 1e30f)) y1 = 0.f; if (!(fabsf(y2) < 1e30f)) y2 = 0.f; if (!(fabsf(y3) < 1e30f)) y3 = 0.f;
;     ...
;             u32x2 o; o.x = pk2(y0, y1); o.y = pk2(y2, y3);
;             *(u32x2*)(Y + row * LDY + ycol + e0) = o; } }
	v_lshlrev_b32_e32 v16, 16, v48
	v_mul_f32_e32 v52, 0xbfb8aa3b, v16
	v_exp_f32_e32 v52, v52
	v_and_b32_e32 v48, 0xffff0000, v48
	v_lshlrev_b32_e32 v51, 16, v49
	v_and_b32_e32 v49, 0xffff0000, v49
	v_mul_f32_e32 v53, 0xbfb8aa3b, v48
	v_mul_f32_e32 v54, 0xbfb8aa3b, v51
	v_mul_f32_e32 v55, 0xbfb8aa3b, v49
	v_exp_f32_e32 v53, v53
	v_add_f32_e32 v52, 1.0, v52
	v_exp_f32_e32 v54, v54
	v_exp_f32_e32 v55, v55
	v_rcp_f32_e32 v52, v52
	v_add_f32_e32 v53, 1.0, v53
	v_pk_mul_f32 v[12:13], v[12:13], v[18:19]
	v_add_f32_e32 v54, 1.0, v54
	v_rcp_f32_e32 v53, v53
	v_add_f32_e32 v55, 1.0, v55
	v_mul_f32_e32 v16, v52, v16
	v_rcp_f32_e32 v54, v54
	v_mul_f32_e32 v12, v12, v16
	v_rcp_f32_e32 v16, v55
	v_mul_f32_e32 v48, v53, v48
	v_pk_mul_f32 v[14:15], v[14:15], v[20:21]
	v_mul_f32_e32 v13, v13, v48
	v_mul_f32_e32 v48, v54, v51
	v_mul_f32_e32 v16, v16, v49
	v_mul_f32_e32 v14, v14, v48
	v_mul_f32_e32 v15, v15, v16
	v_cvt_pk_bf16_f32 v12, v12, v13
	v_cvt_pk_bf16_f32 v13, v14, v15
	v_lshlrev_b64 v[14:15], 11, v[22:23]
	v_lshl_add_u64 v[14:15], v[24:25], 0, v[14:15]
	global_store_dwordx2 v[14:15], v[12:13], off
	v_or_b32_e32 v12, 16, v22
	v_mad_i64_i32 v[14:15], s[0:1], v12, s55, v[28:29]
	v_lshl_add_u64 v[14:15], v[14:15], 0, v[26:27]
	v_mul_f32_e32 v16, 0x4b800000, v50
	v_cndmask_b32_e32 v16, v50, v16, vcc
	v_rsq_f32_e32 v16, v16
	v_mov_b32_e32 v13, s13
	v_or_b32_e32 v48, 32, v22
	v_lshlrev_b64 v[12:13], 11, v[12:13]
	v_mul_f32_e32 v49, 0x45800000, v16
	v_cndmask_b32_e32 v16, v16, v49, vcc
	v_pk_mul_f32 v[8:9], v[8:9], v[16:17] op_sel_hi:[1,0]
	v_pk_mul_f32 v[10:11], v[10:11], v[16:17] op_sel_hi:[1,0]
	v_pk_mul_f32 v[8:9], v[8:9], v[18:19]
	v_mad_i64_i32 v[50:51], s[0:1], v48, s55, v[28:29]
	v_lshl_add_u64 v[12:13], v[24:25], 0, v[12:13]
	v_pk_mul_f32 v[10:11], v[10:11], v[20:21]
	v_lshl_add_u64 v[50:51], v[50:51], 0, v[26:27]
	v_or_b32_e32 v22, 48, v22
	v_lshlrev_b32_e32 v16, 16, v144
	v_and_b32_e32 v14, 0xffff0000, v144
	v_lshlrev_b32_e32 v49, 16, v145
	v_and_b32_e32 v15, 0xffff0000, v145
	v_mul_f32_e32 v52, 0xbfb8aa3b, v16
	v_mul_f32_e32 v53, 0xbfb8aa3b, v14
	v_mul_f32_e32 v54, 0xbfb8aa3b, v49
	v_mul_f32_e32 v55, 0xbfb8aa3b, v15
	v_exp_f32_e32 v52, v52
	v_exp_f32_e32 v53, v53
	v_exp_f32_e32 v54, v54
	v_exp_f32_e32 v55, v55
	v_add_f32_e32 v52, 1.0, v52
	v_add_f32_e32 v53, 1.0, v53
	v_add_f32_e32 v54, 1.0, v54
	v_add_f32_e32 v55, 1.0, v55
	v_rcp_f32_e32 v52, v52
	v_rcp_f32_e32 v53, v53
	v_rcp_f32_e32 v54, v54
	v_rcp_f32_e32 v55, v55
	v_mul_f32_e32 v16, v52, v16
	v_mul_f32_e32 v14, v53, v14
	v_mul_f32_e32 v49, v54, v49
	v_mul_f32_e32 v15, v55, v15
	v_mul_f32_e32 v8, v8, v16
	v_mul_f32_e32 v9, v9, v14
	v_mul_f32_e32 v10, v10, v49
	v_mul_f32_e32 v11, v11, v15
	v_cvt_pk_bf16_f32 v8, v8, v9
	v_cvt_pk_bf16_f32 v9, v10, v11
	global_store_dwordx2 v[12:13], v[8:9], off
	s_waitcnt lgkmcnt(7)
	v_mov_b32_e32 v12, v47
	v_mov_b32_e32 v13, v46
	s_waitcnt lgkmcnt(6)
	v_mov_b32_e32 v14, v45
	v_mov_b32_e32 v15, v44
	v_pk_add_f32 v[12:13], v[12:13], 0 op_sel_hi:[1,0]
	s_waitcnt lgkmcnt(5)
	v_mov_b32_e32 v44, v43
	v_mov_b32_e32 v45, v42
	v_pk_add_f32 v[12:13], v[12:13], v[14:15]
	s_waitcnt lgkmcnt(4)
	v_mov_b32_e32 v42, v41
	v_mov_b32_e32 v43, v40
	v_pk_add_f32 v[12:13], v[12:13], v[44:45]
	s_waitcnt lgkmcnt(3)
	v_mov_b32_e32 v40, v39
	v_mov_b32_e32 v41, v38
	v_pk_add_f32 v[12:13], v[12:13], v[42:43]
	s_waitcnt lgkmcnt(2)
	v_mov_b32_e32 v38, v37
	v_mov_b32_e32 v39, v36
	v_pk_add_f32 v[12:13], v[12:13], v[40:41]
	s_waitcnt lgkmcnt(1)
	v_mov_b32_e32 v36, v35
	v_mov_b32_e32 v37, v34
	v_pk_add_f32 v[12:13], v[12:13], v[38:39]
	s_waitcnt lgkmcnt(0)
	v_mov_b32_e32 v34, v33
	v_mov_b32_e32 v35, v32
	v_pk_add_f32 v[12:13], v[12:13], v[36:37]
	v_mov_b32_e32 v49, s13
	v_pk_add_f32 v[12:13], v[12:13], v[34:35]
	v_lshlrev_b64 v[10:11], 11, v[48:49]
	v_pk_fma_f32 v[12:13], v[12:13], s[10:11], v[30:31] op_sel_hi:[1,0,0]
	v_lshl_add_u64 v[10:11], v[24:25], 0, v[10:11]
	v_mul_f32_e32 v14, 0x4b800000, v13
	v_cmp_gt_f32_e32 vcc, s33, v13
	s_nop 1
	v_cndmask_b32_e32 v13, v13, v14, vcc
	v_rsq_f32_e32 v13, v13
	v_mad_i64_i32 v[14:15], s[0:1], v22, s55, v[28:29]
	v_lshl_add_u64 v[14:15], v[14:15], 0, v[26:27]
	v_mul_f32_e32 v16, 0x45800000, v13
	v_cndmask_b32_e32 v16, v13, v16, vcc
	v_pk_mul_f32 v[4:5], v[4:5], v[16:17] op_sel_hi:[1,0]
	v_pk_mul_f32 v[6:7], v[6:7], v[16:17] op_sel_hi:[1,0]
	v_pk_mul_f32 v[4:5], v[18:19], v[4:5]
	v_pk_mul_f32 v[6:7], v[20:21], v[6:7]
	v_cmp_gt_f32_e32 vcc, s33, v12
	v_lshlrev_b32_e32 v13, 16, v154
	v_and_b32_e32 v8, 0xffff0000, v154
	v_lshlrev_b32_e32 v16, 16, v155
	v_and_b32_e32 v9, 0xffff0000, v155
	v_mul_f32_e32 v26, 0xbfb8aa3b, v13
	v_mul_f32_e32 v27, 0xbfb8aa3b, v8
	v_mul_f32_e32 v28, 0xbfb8aa3b, v16
	v_mul_f32_e32 v29, 0xbfb8aa3b, v9
	v_exp_f32_e32 v26, v26
	v_exp_f32_e32 v27, v27
	v_exp_f32_e32 v28, v28
	v_exp_f32_e32 v29, v29
	v_add_f32_e32 v26, 1.0, v26
	v_add_f32_e32 v27, 1.0, v27
	v_add_f32_e32 v28, 1.0, v28
	v_add_f32_e32 v29, 1.0, v29
	v_rcp_f32_e32 v26, v26
	v_rcp_f32_e32 v27, v27
	v_rcp_f32_e32 v28, v28
	v_rcp_f32_e32 v29, v29
	v_mul_f32_e32 v13, v26, v13
	v_mul_f32_e32 v8, v27, v8
	v_mul_f32_e32 v16, v28, v16
	v_mul_f32_e32 v9, v29, v9
	v_mul_f32_e32 v4, v4, v13
	v_mul_f32_e32 v5, v5, v8
	v_mul_f32_e32 v6, v6, v16
	v_mul_f32_e32 v7, v7, v9
	v_cvt_pk_bf16_f32 v4, v4, v5
	v_cvt_pk_bf16_f32 v5, v6, v7
	global_store_dwordx2 v[10:11], v[4:5], off
	v_mul_f32_e32 v6, 0x4b800000, v12
	v_cndmask_b32_e32 v6, v12, v6, vcc
	v_rsq_f32_e32 v8, v6
	v_lshlrev_b64 v[6:7], 11, v[22:23]
	v_mul_f32_e32 v9, 0x45800000, v8
	v_cndmask_b32_e32 v8, v8, v9, vcc
	v_pk_mul_f32 v[0:1], v[0:1], v[8:9] op_sel_hi:[1,0]
	v_pk_mul_f32 v[2:3], v[2:3], v[8:9] op_sel_hi:[1,0]
	v_pk_mul_f32 v[0:1], v[18:19], v[0:1]
	v_pk_mul_f32 v[2:3], v[20:21], v[2:3]
	v_lshlrev_b32_e32 v8, 16, v168
	v_and_b32_e32 v4, 0xffff0000, v168
	v_lshlrev_b32_e32 v9, 16, v169
	v_and_b32_e32 v5, 0xffff0000, v169
	v_mul_f32_e32 v10, 0xbfb8aa3b, v8
	v_mul_f32_e32 v11, 0xbfb8aa3b, v4
	v_mul_f32_e32 v12, 0xbfb8aa3b, v9
	v_mul_f32_e32 v13, 0xbfb8aa3b, v5
	v_exp_f32_e32 v10, v10
	v_exp_f32_e32 v11, v11
	v_exp_f32_e32 v12, v12
	v_exp_f32_e32 v13, v13
	v_add_f32_e32 v10, 1.0, v10
	v_add_f32_e32 v11, 1.0, v11
	v_add_f32_e32 v12, 1.0, v12
	v_add_f32_e32 v13, 1.0, v13
	v_rcp_f32_e32 v10, v10
	v_rcp_f32_e32 v11, v11
	v_rcp_f32_e32 v12, v12
	v_rcp_f32_e32 v13, v13
	v_mul_f32_e32 v8, v10, v8
	v_mul_f32_e32 v4, v11, v4
	v_mul_f32_e32 v9, v12, v9
	v_mul_f32_e32 v5, v13, v5
	v_mul_f32_e32 v0, v0, v8
	v_mul_f32_e32 v1, v1, v4
	v_mul_f32_e32 v2, v2, v9
	v_mul_f32_e32 v3, v3, v5
	v_cvt_pk_bf16_f32 v0, v0, v1
	v_cvt_pk_bf16_f32 v1, v2, v3
	v_lshl_add_u64 v[2:3], v[24:25], 0, v[6:7]
	global_store_dwordx2 v[2:3], v[0:1], off
	s_waitcnt vmcnt(0) lgkmcnt(0)
	s_barrier

; __device__ __forceinline__ float siluf(float x) { return x * __builtin_amdgcn_rcpf(1.0f + __expf(-x)); }
; #define BSYNC() do { asm volatile("s_waitcnt vmcnt(0) lgkmcnt(0)" ::: "memory"); __syncthreads(); } while (0)
; template <int TY> __device__ __forceinline__ void mc_item(const Params& p, ldsp lds, int item) {
;     ...
;     BSYNC();
; #pragma unroll
;     for (int tk = 0; tk < 4; ++tk) { float s = 0.f;
; #pragma unroll
;         for (int w = 0; w < 8; ++w) s += RED[w * 64 + 16 * tk + l15];
;         rstd[tk] = rsqrtf(s * (1.0f / DV) + EPS); }
;     const float* nwp = TY == 0 ? p.in[12] : (TY == 1 ? p.in[14] : p.in[17]);
;     const int goff = TY == 0 ? E_RA + h * 128 : (TY == 1 ? E_GB + h * 128 : O_G + h * 512);
;     constexpr int LDY = TY == 2 ? 2048 : 1024; const int ycol = TY == 0 ? h * 128 : (TY == 1 ? 512 + h * 128 : h * 512);
;     bf16_t* Y = (bf16_t*)(p.ws + WS_Y);
; #pragma unroll
;     for (int ei = 0; ei < ET; ++ei) { const int e0 = 16 * (wave * ET + ei) + 4 * q4; const f32x4 w4 = *(const f32x4*)(nwp + e0);
; #pragma unroll
;         for (int tk = 0; tk < 4; ++tk) { const size_t row = (size_t)row0 + 16 * tk + l15;
;             const u32x2 gw = *(const u32x2*)(Pb + row * PP + goff + e0);
;             const float g0 = bf2f(gw.x & 0xffffu), g1 = bf2f(gw.x >> 16), g2 = bf2f(gw.y & 0xffffu), g3 = bf2f(gw.y >> 16);
;             const f32x4 v = acc[ei][tk] * rstd[tk] * w4;
;             float y0 = v[0] * siluf(g0), y1 = v[1] * siluf(g1), y2 = v[2] * siluf(g2), y3 = v[3] * siluf(g3);
.LBB0_1281:
	s_or_b64 exec, exec, s[0:1]
	v_lshl_add_u32 v8, v23, 2, 0
	v_add_u32_e32 v16, 0x13800, v8
	s_waitcnt vmcnt(0) lgkmcnt(0)
	s_waitcnt lgkmcnt(0)
	s_barrier
	ds_read2_b32 v[8:9], v16 offset1:16
	ds_read2_b32 v[10:11], v16 offset0:64 offset1:80
	ds_read2_b32 v[26:27], v16 offset0:128 offset1:144
	ds_read2_b32 v[28:29], v16 offset0:192 offset1:208
	v_add_u32_e32 v22, 0x400, v16
	s_waitcnt lgkmcnt(3)
	v_mov_b32_e32 v38, v9
	v_mov_b32_e32 v39, v8
	v_pk_add_f32 v[8:9], v[38:39], 0 op_sel_hi:[1,0]
	s_waitcnt lgkmcnt(2)
	v_mov_b32_e32 v38, v11
	v_mov_b32_e32 v39, v10
	ds_read2_b32 v[30:31], v22 offset1:16
	ds_read2_b32 v[32:33], v22 offset0:64 offset1:80
	ds_read2_b32 v[34:35], v22 offset0:128 offset1:144
	ds_read2_b32 v[36:37], v22 offset0:192 offset1:208
	v_pk_add_f32 v[8:9], v[8:9], v[38:39]
	s_waitcnt lgkmcnt(5)
	v_mov_b32_e32 v10, v27
	v_mov_b32_e32 v11, v26
	v_pk_add_f32 v[8:9], v[8:9], v[10:11]
	s_waitcnt lgkmcnt(4)
	v_mov_b32_e32 v10, v29
	v_mov_b32_e32 v11, v28
	v_pk_add_f32 v[8:9], v[8:9], v[10:11]
	s_waitcnt lgkmcnt(3)
	v_mov_b32_e32 v10, v31
	v_mov_b32_e32 v11, v30
	v_pk_add_f32 v[8:9], v[8:9], v[10:11]
	s_waitcnt lgkmcnt(2)
	v_mov_b32_e32 v10, v33
	v_mov_b32_e32 v11, v32
	v_pk_add_f32 v[8:9], v[8:9], v[10:11]
	s_waitcnt lgkmcnt(1)
	v_mov_b32_e32 v10, v35
	v_mov_b32_e32 v11, v34
	v_pk_add_f32 v[8:9], v[8:9], v[10:11]
	s_waitcnt lgkmcnt(0)
	v_mov_b32_e32 v10, v37
	v_mov_b32_e32 v11, v36
	s_mov_b32 s0, 0x358637bd
	v_pk_add_f32 v[8:9], v[8:9], v[10:11]
	v_mov_b64_e32 v[10:11], s[0:1]
	s_brev_b32 s12, 60
	v_pk_fma_f32 v[8:9], v[8:9], s[12:13], v[10:11] op_sel_hi:[1,0,0]
	v_or_b32_e32 v24, s11, v24
	v_mul_f32_e32 v25, 0x4b800000, v9
	v_cmp_gt_f32_e64 s[0:1], s33, v9
	v_cmp_gt_f32_e32 vcc, s33, v8
	v_readlane_b32 s76, v252, 20
	v_cndmask_b32_e64 v9, v9, v25, s[0:1]
	v_rsq_f32_e32 v9, v9
	v_readlane_b32 s88, v252, 32
	v_readlane_b32 s89, v252, 33
	v_readlane_b32 s77, v252, 21
	v_mul_f32_e32 v25, 0x45800000, v9
	v_cndmask_b32_e64 v32, v9, v25, s[0:1]
	v_mul_f32_e32 v9, 0x4b800000, v8
	v_cndmask_b32_e32 v8, v8, v9, vcc
	v_rsq_f32_e32 v8, v8
	v_ashrrev_i32_e32 v25, 31, v24
	v_readlane_b32 s78, v252, 22
	v_readlane_b32 s79, v252, 23
	v_mul_f32_e32 v9, 0x45800000, v8
	v_cndmask_b32_e32 v30, v8, v9, vcc
	ds_read2_b32 v[8:9], v16 offset0:32 offset1:48
	ds_read2_b32 v[26:27], v16 offset0:96 offset1:112
	ds_read2_b32 v[28:29], v16 offset0:160 offset1:176
	ds_read2_b32 v[34:35], v16 offset0:224 offset1:240
	ds_read2_b32 v[36:37], v22 offset0:32 offset1:48
	ds_read2_b32 v[38:39], v22 offset0:96 offset1:112
	ds_read2_b32 v[40:41], v22 offset0:160 offset1:176
	ds_read2_b32 v[42:43], v22 offset0:224 offset1:240
	s_waitcnt lgkmcnt(7)
	v_mov_b32_e32 v44, v9
	v_mov_b32_e32 v45, v8
	v_pk_add_f32 v[8:9], v[44:45], 0 op_sel_hi:[1,0]
	s_waitcnt lgkmcnt(6)
	v_mov_b32_e32 v44, v27
	v_mov_b32_e32 v45, v26
	v_pk_add_f32 v[8:9], v[8:9], v[44:45]
	s_waitcnt lgkmcnt(5)
	v_mov_b32_e32 v26, v29
	v_mov_b32_e32 v27, v28
	v_pk_add_f32 v[8:9], v[8:9], v[26:27]
	s_waitcnt lgkmcnt(4)
	v_mov_b32_e32 v26, v35
	v_mov_b32_e32 v27, v34
	v_pk_add_f32 v[8:9], v[8:9], v[26:27]
	s_waitcnt lgkmcnt(3)
	v_mov_b32_e32 v26, v37
	v_mov_b32_e32 v27, v36
	v_pk_add_f32 v[8:9], v[8:9], v[26:27]
	s_waitcnt lgkmcnt(2)
	v_mov_b32_e32 v26, v39
	v_mov_b32_e32 v27, v38
	v_pk_add_f32 v[8:9], v[8:9], v[26:27]
	s_waitcnt lgkmcnt(1)
	v_mov_b32_e32 v26, v41
	v_mov_b32_e32 v27, v40
	v_pk_add_f32 v[8:9], v[8:9], v[26:27]
	s_waitcnt lgkmcnt(0)
	v_mov_b32_e32 v26, v43
	v_mov_b32_e32 v27, v42
	v_pk_add_f32 v[8:9], v[8:9], v[26:27]
	v_or_b32_e32 v16, s9, v23
	v_pk_fma_f32 v[8:9], v[8:9], s[12:13], v[10:11] op_sel_hi:[1,0,0]
	s_add_u32 s12, s26, s10
	v_mul_f32_e32 v10, 0x4b800000, v9
	v_cmp_gt_f32_e64 s[0:1], s33, v9
	v_cmp_gt_f32_e32 vcc, s33, v8
	s_addc_u32 s13, s27, 0
	v_cndmask_b32_e64 v9, v9, v10, s[0:1]
	v_rsq_f32_e32 v9, v9
	v_mov_b64_e32 v[28:29], s[12:13]
	s_mov_b32 s9, 0x1ec21000
	v_readlane_b32 s80, v252, 24
	v_mul_f32_e32 v10, 0x45800000, v9
	v_cndmask_b32_e64 v26, v9, v10, s[0:1]
	v_mul_f32_e32 v9, 0x4b800000, v8
	v_cndmask_b32_e32 v8, v8, v9, vcc
	v_rsq_f32_e32 v8, v8
	s_add_u32 s0, s68, s10
	v_mad_u64_u32 v[34:35], s[10:11], v16, s55, v[28:29]
	v_mul_f32_e32 v9, 0x45800000, v8
	v_cndmask_b32_e32 v22, v8, v9, vcc
	v_lshl_add_u64 v[8:9], v[24:25], 2, s[88:89]
	v_lshlrev_b64 v[24:25], 1, v[24:25]
	v_lshl_add_u64 v[34:35], v[34:35], 0, v[24:25]
	v_add_co_u32_e32 v34, vcc, s57, v34
	global_load_dwordx4 v[8:11], v[8:9], off
	s_nop 0
	v_addc_co_u32_e32 v35, vcc, 0, v35, vcc
	global_load_dwordx2 v[34:35], v[34:35], off offset:2048
	s_mov_b32 s98, s57
	s_mov_b32 s99, 0
	v_or_b32_e32 v64, 16, v16
	v_mad_u64_u32 v[134:135], s[10:11], v64, s55, v[28:29]
	v_lshl_add_u64 v[140:141], v[134:135], 0, v[24:25]
	v_lshl_add_u64 v[142:143], v[140:141], 0, s[98:99]
	global_load_dwordx2 v[144:145], v[142:143], off offset:2048
	v_or_b32_e32 v146, 32, v16
	v_mad_u64_u32 v[148:149], s[10:11], v146, s55, v[28:29]
	v_lshl_add_u64 v[150:151], v[148:149], 0, v[24:25]
	v_lshl_add_u64 v[152:153], v[150:151], 0, s[98:99]
	global_load_dwordx2 v[154:155], v[152:153], off offset:2048
	v_or_b32_e32 v156, 48, v16
	v_mad_u64_u32 v[166:167], s[10:11], v156, s55, v[28:29]
	v_lshl_add_u64 v[168:169], v[166:167], 0, v[24:25]
	v_lshl_add_u64 v[172:173], v[168:169], 0, s[98:99]
	global_load_dwordx2 v[174:175], v[172:173], off offset:2048
	s_addc_u32 s1, s69, 0
	v_readlane_b32 s81, v252, 25
	v_readlane_b32 s82, v252, 26
	v_readlane_b32 s83, v252, 27
	v_readlane_b32 s84, v252, 28
	v_readlane_b32 s85, v252, 29
	v_readlane_b32 s86, v252, 30
	v_readlane_b32 s87, v252, 31
	v_readlane_b32 s90, v252, 34
	v_readlane_b32 s91, v252, 35
	s_waitcnt vmcnt(0)
; __device__ __forceinline__ unsigned pk2(float lo, float hi) { return pg8::cvt_pk_bf16(lo, hi); }
; __device__ __forceinline__ float siluf(float x) { return x * __builtin_amdgcn_rcpf(1.0f + __expf(-x)); }
; template <int TY> __device__ __forceinline__ void mc_item(const Params& p, ldsp lds, int item) {
;     ...
;     for (int ei = 0; ei < ET; ++ei) { const int e0 = 16 * (wave * ET + ei) + 4 * q4; const f32x4 w4 = *(const f32x4*)(nwp + e0);
; #pragma unroll
;         for (int tk = 0; tk < 4; ++tk) { const size_t row = (size_t)row0 + 16 * tk + l15;
;             const u32x2 gw = *(const u32x2*)(Pb + row * PP + goff + e0);
;             const float g0 = bf2f(gw.x & 0xffffu), g1 = bf2f(gw.x >> 16), g2 = bf2f(gw.y & 0xffffu), g3 = bf2f(gw.y >> 16);
;             const f32x4 v = acc[ei][tk] * rstd[tk] * w4;
;             float y0 = v[0] * siluf(g0), y1 = v[1] * siluf(g1), y2 = v[2] * siluf(g2), y3 = v[3] * siluf(g3);
;     ...
;             if (!(fabsf(y0) < 1e30f)) y0 = 0.f; if (!(fabsf(y1) < 1e30f)) y1 = 0.f; if (!(fabsf(y2) < 1e30f)) y2 = 0.f; if (!(fabsf(y3) < 1e30f)) y3 = 0.f;
;     ...
;             u32x2 o; o.x = pk2(y0, y1); o.y = pk2(y2, y3);
;             *(u32x2*)(Y + row * LDY + ycol + e0) = o; } }
	v_lshlrev_b32_e32 v23, 16, v34
	v_and_b32_e32 v33, 0xffff0000, v35
	v_pk_mul_f32 v[18:19], v[18:19], v[32:33] op_sel_hi:[1,0]
	v_pk_mul_f32 v[20:21], v[20:21], v[32:33] op_sel_hi:[1,0]
	v_mul_f32_e32 v32, 0xbfb8aa3b, v23
	v_exp_f32_e32 v32, v32
	v_and_b32_e32 v27, 0xffff0000, v34
	v_pk_mul_f32 v[18:19], v[18:19], v[8:9]
	v_lshlrev_b32_e32 v31, 16, v35
	v_add_f32_e32 v32, 1.0, v32
	v_rcp_f32_e32 v32, v32
	v_pk_mul_f32 v[20:21], v[20:21], v[10:11]
	v_pk_mul_f32 v[12:13], v[12:13], v[30:31] op_sel_hi:[1,0]
	v_pk_mul_f32 v[14:15], v[14:15], v[30:31] op_sel_hi:[1,0]
	v_mul_f32_e32 v23, v32, v23
	v_mul_f32_e32 v18, v18, v23
	v_mul_f32_e32 v23, 0xbfb8aa3b, v27
	v_exp_f32_e32 v23, v23
	v_pk_mul_f32 v[12:13], v[12:13], v[8:9]
	v_pk_mul_f32 v[14:15], v[14:15], v[10:11]
	v_add_f32_e32 v23, 1.0, v23
	v_rcp_f32_e32 v23, v23
	s_nop 0
	v_mul_f32_e32 v23, v23, v27
	v_mul_f32_e32 v19, v19, v23
	v_mul_f32_e32 v23, 0xbfb8aa3b, v31
	v_exp_f32_e32 v23, v23
	v_cvt_pk_bf16_f32 v18, v18, v19
	s_nop 0
	v_add_f32_e32 v23, 1.0, v23
	v_rcp_f32_e32 v23, v23
	s_nop 0
	v_mul_f32_e32 v23, v23, v31
	v_mul_f32_e32 v20, v20, v23
	v_mul_f32_e32 v23, 0xbfb8aa3b, v33
	v_exp_f32_e32 v23, v23
	s_nop 0
	v_add_f32_e32 v23, 1.0, v23
	v_rcp_f32_e32 v23, v23
	s_nop 0
	v_mul_f32_e32 v23, v23, v33
	v_mul_f32_e32 v21, v21, v23
	v_cvt_pk_bf16_f32 v19, v20, v21
	v_lshlrev_b64 v[20:21], 11, v[16:17]
	v_lshl_add_u64 v[20:21], s[0:1], 0, v[20:21]
	v_lshl_add_u64 v[20:21], v[20:21], 0, v[24:25]
	v_add_co_u32_e32 v20, vcc, s9, v20
	s_nop 1
	v_addc_co_u32_e32 v21, vcc, 0, v21, vcc
	global_store_dwordx2 v[20:21], v[18:19], off offset:1024
	v_or_b32_e32 v18, 16, v16
	v_mad_u64_u32 v[20:21], s[10:11], v18, s55, v[28:29]
	v_lshl_add_u64 v[20:21], v[20:21], 0, v[24:25]
	s_nop 0
	v_mov_b32_e32 v19, v17
	s_nop 0
	v_lshl_add_u64 v[20:21], v[20:21], 0, s[98:99]
	v_lshlrev_b32_e32 v23, 16, v144
	v_mul_f32_e32 v30, 0xbfb8aa3b, v23
	v_exp_f32_e32 v30, v30
	v_and_b32_e32 v20, 0xffff0000, v144
	v_lshlrev_b32_e32 v27, 16, v145
	v_and_b32_e32 v21, 0xffff0000, v145
	v_add_f32_e32 v30, 1.0, v30
	v_rcp_f32_e32 v30, v30
	v_pk_mul_f32 v[4:5], v[4:5], v[26:27] op_sel_hi:[1,0]
	v_pk_mul_f32 v[6:7], v[6:7], v[26:27] op_sel_hi:[1,0]
	v_pk_mul_f32 v[4:5], v[8:9], v[4:5]
	v_mul_f32_e32 v23, v30, v23
	v_mul_f32_e32 v12, v12, v23
	v_mul_f32_e32 v23, 0xbfb8aa3b, v20
	v_exp_f32_e32 v23, v23
	v_pk_mul_f32 v[6:7], v[10:11], v[6:7]
	v_add_f32_e32 v23, 1.0, v23
	v_rcp_f32_e32 v23, v23
	s_nop 0
	v_mul_f32_e32 v20, v23, v20
	v_mul_f32_e32 v13, v13, v20
	v_mul_f32_e32 v20, 0xbfb8aa3b, v27
	v_exp_f32_e32 v20, v20
	v_cvt_pk_bf16_f32 v12, v12, v13
	v_pk_mul_f32 v[0:1], v[0:1], v[22:23] op_sel_hi:[1,0]
	v_pk_mul_f32 v[2:3], v[2:3], v[22:23] op_sel_hi:[1,0]
	v_add_f32_e32 v20, 1.0, v20
	v_rcp_f32_e32 v20, v20
	v_pk_mul_f32 v[0:1], v[8:9], v[0:1]
	v_pk_mul_f32 v[2:3], v[10:11], v[2:3]
	v_mul_f32_e32 v20, v20, v27
	v_mul_f32_e32 v14, v14, v20
	v_mul_f32_e32 v20, 0xbfb8aa3b, v21
	v_exp_f32_e32 v20, v20
	s_nop 0
	v_add_f32_e32 v20, 1.0, v20
	v_rcp_f32_e32 v20, v20
	s_nop 0
	v_mul_f32_e32 v20, v20, v21
	v_mul_f32_e32 v15, v15, v20
	v_cvt_pk_bf16_f32 v13, v14, v15
	v_lshlrev_b64 v[14:15], 11, v[18:19]
	v_lshl_add_u64 v[14:15], s[0:1], 0, v[14:15]
	v_lshl_add_u64 v[14:15], v[14:15], 0, v[24:25]
	v_add_co_u32_e32 v14, vcc, s9, v14
	s_nop 1
	v_addc_co_u32_e32 v15, vcc, 0, v15, vcc
	global_store_dwordx2 v[14:15], v[12:13], off offset:1024
	v_or_b32_e32 v12, 32, v16
	v_mad_u64_u32 v[14:15], s[10:11], v12, s55, v[28:29]
	v_lshl_add_u64 v[14:15], v[14:15], 0, v[24:25]
	s_nop 0
	v_mov_b32_e32 v13, v17
	s_nop 0
	v_lshl_add_u64 v[14:15], v[14:15], 0, s[98:99]
	v_or_b32_e32 v16, 48, v16
	v_lshlrev_b32_e32 v18, 16, v154
	v_mul_f32_e32 v20, 0xbfb8aa3b, v18
	v_exp_f32_e32 v20, v20
	v_and_b32_e32 v14, 0xffff0000, v154
	v_lshlrev_b32_e32 v19, 16, v155
	v_and_b32_e32 v15, 0xffff0000, v155
	v_add_f32_e32 v20, 1.0, v20
	v_rcp_f32_e32 v20, v20
	s_nop 0
	v_mul_f32_e32 v18, v20, v18
	v_mul_f32_e32 v4, v4, v18
	v_mul_f32_e32 v18, 0xbfb8aa3b, v14
	v_exp_f32_e32 v18, v18
	s_nop 0
	v_add_f32_e32 v18, 1.0, v18
	v_rcp_f32_e32 v18, v18
	s_nop 0
	v_mul_f32_e32 v14, v18, v14
	v_mul_f32_e32 v5, v5, v14
	v_mul_f32_e32 v14, 0xbfb8aa3b, v19
	v_exp_f32_e32 v14, v14
	v_cvt_pk_bf16_f32 v4, v4, v5
	s_nop 0
	v_add_f32_e32 v14, 1.0, v14
	v_rcp_f32_e32 v14, v14
	s_nop 0
	v_mul_f32_e32 v14, v14, v19
	v_mul_f32_e32 v6, v6, v14
	v_mul_f32_e32 v14, 0xbfb8aa3b, v15
	v_exp_f32_e32 v14, v14
	s_nop 0
	v_add_f32_e32 v14, 1.0, v14
	v_rcp_f32_e32 v14, v14
	s_nop 0
	v_mul_f32_e32 v14, v14, v15
	v_mul_f32_e32 v7, v7, v14
	v_cvt_pk_bf16_f32 v5, v6, v7
	v_lshlrev_b64 v[6:7], 11, v[12:13]
	v_lshl_add_u64 v[6:7], s[0:1], 0, v[6:7]
	v_lshl_add_u64 v[6:7], v[6:7], 0, v[24:25]
	v_add_co_u32_e32 v6, vcc, s9, v6
	s_nop 1
	v_addc_co_u32_e32 v7, vcc, 0, v7, vcc
	global_store_dwordx2 v[6:7], v[4:5], off offset:1024
	v_mad_u64_u32 v[4:5], s[10:11], v16, s55, v[28:29]
	v_lshl_add_u64 v[4:5], v[4:5], 0, v[24:25]
	s_nop 0
	s_nop 1
	v_lshl_add_u64 v[4:5], v[4:5], 0, s[98:99]
	v_lshlrev_b32_e32 v6, 16, v174
	v_mul_f32_e32 v8, 0xbfb8aa3b, v6
	v_exp_f32_e32 v8, v8
	v_and_b32_e32 v4, 0xffff0000, v174
	v_lshlrev_b32_e32 v7, 16, v175
	v_and_b32_e32 v5, 0xffff0000, v175
	v_add_f32_e32 v8, 1.0, v8
	v_rcp_f32_e32 v8, v8
	s_nop 0
	v_mul_f32_e32 v6, v8, v6
	v_mul_f32_e32 v0, v0, v6
	v_mul_f32_e32 v6, 0xbfb8aa3b, v4
	v_exp_f32_e32 v6, v6
	s_nop 0
	v_add_f32_e32 v6, 1.0, v6
	v_rcp_f32_e32 v6, v6
	s_nop 0
	v_mul_f32_e32 v4, v6, v4
	v_mul_f32_e32 v1, v1, v4
	v_mul_f32_e32 v4, 0xbfb8aa3b, v7
	v_exp_f32_e32 v4, v4
	v_cvt_pk_bf16_f32 v0, v0, v1
	s_nop 0
	v_add_f32_e32 v4, 1.0, v4
	v_rcp_f32_e32 v4, v4
	s_nop 0
	v_mul_f32_e32 v4, v4, v7
	v_mul_f32_e32 v2, v2, v4
	v_mul_f32_e32 v4, 0xbfb8aa3b, v5
	v_exp_f32_e32 v4, v4
	s_nop 0
	v_add_f32_e32 v4, 1.0, v4
	v_rcp_f32_e32 v4, v4
	s_nop 0
	v_mul_f32_e32 v4, v4, v5
	v_mul_f32_e32 v3, v3, v4
	v_cvt_pk_bf16_f32 v1, v2, v3
	v_lshlrev_b64 v[2:3], 11, v[16:17]
	v_lshl_add_u64 v[2:3], s[0:1], 0, v[2:3]
	v_lshl_add_u64 v[2:3], v[2:3], 0, v[24:25]
	v_add_co_u32_e32 v2, vcc, 0x1ec21000, v2
	s_nop 1
	v_addc_co_u32_e32 v3, vcc, 0, v3, vcc
	global_store_dwordx2 v[2:3], v[0:1], off offset:1024
	s_waitcnt vmcnt(0) lgkmcnt(0)
	s_barrier
	s_branch .LBB0_1267
